# G4 SwiGLU epilogue: per-element dependent chains issued stage by stage (no s_nop pads), on top of the attention row-max and bias-table edits
# baseline (speedup 1.0000x reference)
; __device__ __forceinline__ unsigned cvt_pk_bf16(float lo, float hi) { unsigned r; asm volatile("v_cvt_pk_bf16_f32 %0, %1, %2" : "=v"(r) : "v"(lo), "v"(hi)); return r; }
; __device__ __forceinline__ float sigmoidf_(float x) { return __builtin_amdgcn_rcpf(1.0f + __builtin_amdgcn_exp2f(-1.4426950408889634f * x)); }
;     __device__ __forceinline__ void operator()(const Acc& acc, const Unit& u, int wr, int wc, int fr, int fq) const {
;         const int row0 = u.pm * 256 + wr * 64 + fr; const int col = u.pn * 128 + wc * 32 + 8 * fq;
; #pragma unroll
;         for (int ai = 0; ai < 2; ++ai)
; #pragma unroll
;             for (int m = 0; m < 4; ++m) {
;                 float o[8];
; #pragma unroll
;                 for (int j = 0; j < 8; ++j) { const float g = acc[ai][0][m][j >> 2][j & 3], up = acc[ai][1][m][j >> 2][j & 3]; o[j] = g * sigmoidf_(g) * up; }
;                 u32x4 w; w.x = cvt_pk_bf16(o[0], o[1]); w.y = cvt_pk_bf16(o[2], o[3]); w.z = cvt_pk_bf16(o[4], o[5]); w.w = cvt_pk_bf16(o[6], o[7]);
;                 *(u32x4*)(hid + (size_t)(row0 + ai * 128 + m * 16) * DFF + col) = w;
;             }
.LBB0_1652:
	v_mov_b32_e32 v143, v208
	s_lshl_b32 s31, s31, 8
	v_readfirstlane_b32 s19, v143
	s_ashr_i32 s34, s19, 2
	s_andn2_b32 s34, s34, 63
	s_lshr_b32 s19, s19, 1
	s_add_i32 s34, s34, s31
	s_lshl_b32 s30, s30, 7
	s_and_b32 s19, s19, 0x60
	v_and_or_b32 v142, v143, 15, s34
	s_or_b32 s19, s19, s30
	v_lshrrev_b32_e32 v143, 1, v143
	v_and_or_b32 v144, v143, 24, s19
	v_ashrrev_i32_e32 v145, 31, v144
	s_movk_i32 s19, 0x2c00
	s_andn2_b64 vcc, exec, s[16:17]
	v_mul_f32_e32 v146, 0xbfb8aa3b, v126
	v_mul_f32_e32 v147, 0xbfb8aa3b, v127
	v_mul_f32_e32 v148, 0xbfb8aa3b, v128
	v_mul_f32_e32 v149, 0xbfb8aa3b, v129
	v_mul_f32_e32 v150, 0xbfb8aa3b, v118
	v_mul_f32_e32 v151, 0xbfb8aa3b, v119
	v_mul_f32_e32 v152, 0xbfb8aa3b, v120
	v_mul_f32_e32 v153, 0xbfb8aa3b, v121
	v_exp_f32_e32 v146, v146
	v_exp_f32_e32 v147, v147
	v_exp_f32_e32 v148, v148
	v_exp_f32_e32 v149, v149
	v_exp_f32_e32 v150, v150
	v_exp_f32_e32 v151, v151
	v_exp_f32_e32 v152, v152
	v_exp_f32_e32 v153, v153
	v_add_f32_e32 v146, 1.0, v146
	v_add_f32_e32 v147, 1.0, v147
	v_add_f32_e32 v148, 1.0, v148
	v_add_f32_e32 v149, 1.0, v149
	v_add_f32_e32 v150, 1.0, v150
	v_add_f32_e32 v151, 1.0, v151
	v_add_f32_e32 v152, 1.0, v152
	v_add_f32_e32 v153, 1.0, v153
	v_rcp_f32_e32 v146, v146
	v_rcp_f32_e32 v147, v147
	v_rcp_f32_e32 v148, v148
	v_rcp_f32_e32 v149, v149
	v_rcp_f32_e32 v150, v150
	v_rcp_f32_e32 v151, v151
	v_rcp_f32_e32 v152, v152
	v_rcp_f32_e32 v153, v153
	v_mul_f32_e32 v146, v126, v146
	v_mul_f32_e32 v147, v127, v147
	v_mul_f32_e32 v148, v128, v148
	v_mul_f32_e32 v149, v129, v149
	v_mul_f32_e32 v150, v118, v150
	v_mul_f32_e32 v151, v119, v151
	v_mul_f32_e32 v152, v120, v152
	v_mul_f32_e32 v153, v121, v153
	v_mul_f32_e32 v122, v122, v146
	v_mul_f32_e32 v123, v123, v147
	v_mul_f32_e32 v124, v124, v148
	v_mul_f32_e32 v125, v125, v149
	v_mul_f32_e32 v114, v114, v150
	v_mul_f32_e32 v115, v115, v151
	v_mul_f32_e32 v116, v116, v152
	v_mul_f32_e32 v117, v117, v153
	v_cvt_pk_bf16_f32 v118, v122, v123
	v_cvt_pk_bf16_f32 v119, v124, v125
	v_cvt_pk_bf16_f32 v120, v114, v115
	v_mov_b64_e32 v[114:115], s[4:5]
	v_cvt_pk_bf16_f32 v121, v116, v117
	v_mad_i64_i32 v[122:123], s[30:31], v142, s19, v[114:115]
	v_lshlrev_b64 v[116:117], 1, v[144:145]
	v_lshl_add_u64 v[122:123], v[122:123], 0, v[116:117]
	global_store_dwordx4 v[122:123], v[118:121], off
	s_nop 1
	v_mul_f32_e32 v146, 0xbfb8aa3b, v110
	v_mul_f32_e32 v147, 0xbfb8aa3b, v111
	v_mul_f32_e32 v148, 0xbfb8aa3b, v112
	v_mul_f32_e32 v149, 0xbfb8aa3b, v113
	v_mul_f32_e32 v150, 0xbfb8aa3b, v102
	v_mul_f32_e32 v151, 0xbfb8aa3b, v103
	v_mul_f32_e32 v152, 0xbfb8aa3b, v104
	v_mul_f32_e32 v153, 0xbfb8aa3b, v105
	v_exp_f32_e32 v146, v146
	v_exp_f32_e32 v147, v147
	v_exp_f32_e32 v148, v148
	v_exp_f32_e32 v149, v149
	v_exp_f32_e32 v150, v150
	v_exp_f32_e32 v151, v151
	v_exp_f32_e32 v152, v152
	v_exp_f32_e32 v153, v153
	v_add_f32_e32 v146, 1.0, v146
	v_add_f32_e32 v147, 1.0, v147
	v_add_f32_e32 v148, 1.0, v148
	v_add_f32_e32 v149, 1.0, v149
	v_add_f32_e32 v150, 1.0, v150
	v_add_f32_e32 v151, 1.0, v151
	v_add_f32_e32 v152, 1.0, v152
	v_add_f32_e32 v153, 1.0, v153
	v_rcp_f32_e32 v146, v146
	v_rcp_f32_e32 v147, v147
	v_rcp_f32_e32 v148, v148
	v_rcp_f32_e32 v149, v149
	v_rcp_f32_e32 v150, v150
	v_rcp_f32_e32 v151, v151
	v_rcp_f32_e32 v152, v152
	v_rcp_f32_e32 v153, v153
	v_mul_f32_e32 v146, v110, v146
	v_mul_f32_e32 v147, v111, v147
	v_mul_f32_e32 v148, v112, v148
	v_mul_f32_e32 v149, v113, v149
	v_mul_f32_e32 v150, v102, v150
	v_mul_f32_e32 v151, v103, v151
	v_mul_f32_e32 v152, v104, v152
	v_mul_f32_e32 v153, v105, v153
	v_mul_f32_e32 v106, v106, v146
	v_mul_f32_e32 v107, v107, v147
	v_mul_f32_e32 v108, v108, v148
	v_mul_f32_e32 v109, v109, v149
	v_mul_f32_e32 v102, v98, v150
	v_mul_f32_e32 v103, v99, v151
	v_mul_f32_e32 v104, v100, v152
	v_mul_f32_e32 v101, v101, v153
	v_cvt_pk_bf16_f32 v98, v106, v107
	v_cvt_pk_bf16_f32 v99, v108, v109
	v_cvt_pk_bf16_f32 v100, v102, v103
	v_or_b32_e32 v102, 16, v142
	v_mad_i64_i32 v[102:103], s[30:31], v102, s19, v[114:115]
	v_lshl_add_u64 v[102:103], v[102:103], 0, v[116:117]
	v_cvt_pk_bf16_f32 v101, v104, v101
	global_store_dwordx4 v[102:103], v[98:101], off
	s_nop 1
	v_mul_f32_e32 v146, 0xbfb8aa3b, v94
	v_mul_f32_e32 v147, 0xbfb8aa3b, v95
	v_mul_f32_e32 v148, 0xbfb8aa3b, v96
	v_mul_f32_e32 v149, 0xbfb8aa3b, v97
	v_mul_f32_e32 v150, 0xbfb8aa3b, v86
	v_mul_f32_e32 v151, 0xbfb8aa3b, v87
	v_mul_f32_e32 v152, 0xbfb8aa3b, v88
	v_mul_f32_e32 v153, 0xbfb8aa3b, v89
	v_exp_f32_e32 v146, v146
	v_exp_f32_e32 v147, v147
	v_exp_f32_e32 v148, v148
	v_exp_f32_e32 v149, v149
	v_exp_f32_e32 v150, v150
	v_exp_f32_e32 v151, v151
	v_exp_f32_e32 v152, v152
	v_exp_f32_e32 v153, v153
	v_add_f32_e32 v146, 1.0, v146
	v_add_f32_e32 v147, 1.0, v147
	v_add_f32_e32 v148, 1.0, v148
	v_add_f32_e32 v149, 1.0, v149
	v_add_f32_e32 v150, 1.0, v150
	v_add_f32_e32 v151, 1.0, v151
	v_add_f32_e32 v152, 1.0, v152
	v_add_f32_e32 v153, 1.0, v153
	v_rcp_f32_e32 v146, v146
	v_rcp_f32_e32 v147, v147
	v_rcp_f32_e32 v148, v148
	v_rcp_f32_e32 v149, v149
	v_rcp_f32_e32 v150, v150
	v_rcp_f32_e32 v151, v151
	v_rcp_f32_e32 v152, v152
	v_rcp_f32_e32 v153, v153
	v_mul_f32_e32 v146, v94, v146
	v_mul_f32_e32 v147, v95, v147
	v_mul_f32_e32 v148, v96, v148
	v_mul_f32_e32 v149, v97, v149
	v_mul_f32_e32 v150, v86, v150
	v_mul_f32_e32 v151, v87, v151
	v_mul_f32_e32 v152, v88, v152
	v_mul_f32_e32 v153, v89, v153
	v_mul_f32_e32 v90, v90, v146
	v_mul_f32_e32 v91, v91, v147
	v_mul_f32_e32 v92, v92, v148
	v_mul_f32_e32 v93, v93, v149
	v_mul_f32_e32 v86, v82, v150
	v_mul_f32_e32 v87, v83, v151
	v_mul_f32_e32 v88, v84, v152
	v_mul_f32_e32 v85, v85, v153
	v_cvt_pk_bf16_f32 v82, v90, v91
; __device__ __forceinline__ unsigned cvt_pk_bf16(float lo, float hi) { unsigned r; asm volatile("v_cvt_pk_bf16_f32 %0, %1, %2" : "=v"(r) : "v"(lo), "v"(hi)); return r; }
; __device__ __forceinline__ float sigmoidf_(float x) { return __builtin_amdgcn_rcpf(1.0f + __builtin_amdgcn_exp2f(-1.4426950408889634f * x)); }
;     __device__ __forceinline__ void operator()(const Acc& acc, const Unit& u, int wr, int wc, int fr, int fq) const {
;         const int row0 = u.pm * 256 + wr * 64 + fr; const int col = u.pn * 128 + wc * 32 + 8 * fq;
; #pragma unroll
;         for (int ai = 0; ai < 2; ++ai)
; #pragma unroll
;             for (int m = 0; m < 4; ++m) {
;                 float o[8];
; #pragma unroll
;                 for (int j = 0; j < 8; ++j) { const float g = acc[ai][0][m][j >> 2][j & 3], up = acc[ai][1][m][j >> 2][j & 3]; o[j] = g * sigmoidf_(g) * up; }
;                 u32x4 w; w.x = cvt_pk_bf16(o[0], o[1]); w.y = cvt_pk_bf16(o[2], o[3]); w.z = cvt_pk_bf16(o[4], o[5]); w.w = cvt_pk_bf16(o[6], o[7]);
;                 *(u32x4*)(hid + (size_t)(row0 + ai * 128 + m * 16) * DFF + col) = w;
;             }
	v_cvt_pk_bf16_f32 v83, v92, v93
	v_cvt_pk_bf16_f32 v84, v86, v87
	v_or_b32_e32 v86, 32, v142
	v_mad_i64_i32 v[86:87], s[30:31], v86, s19, v[114:115]
	v_lshl_add_u64 v[86:87], v[86:87], 0, v[116:117]
	v_cvt_pk_bf16_f32 v85, v88, v85
	global_store_dwordx4 v[86:87], v[82:85], off
	s_nop 1
	v_mul_f32_e32 v146, 0xbfb8aa3b, v78
	v_mul_f32_e32 v147, 0xbfb8aa3b, v79
	v_mul_f32_e32 v148, 0xbfb8aa3b, v80
	v_mul_f32_e32 v149, 0xbfb8aa3b, v81
	v_mul_f32_e32 v150, 0xbfb8aa3b, v70
	v_mul_f32_e32 v151, 0xbfb8aa3b, v71
	v_mul_f32_e32 v152, 0xbfb8aa3b, v72
	v_mul_f32_e32 v153, 0xbfb8aa3b, v73
	v_exp_f32_e32 v146, v146
	v_exp_f32_e32 v147, v147
	v_exp_f32_e32 v148, v148
	v_exp_f32_e32 v149, v149
	v_exp_f32_e32 v150, v150
	v_exp_f32_e32 v151, v151
	v_exp_f32_e32 v152, v152
	v_exp_f32_e32 v153, v153
	v_add_f32_e32 v146, 1.0, v146
	v_add_f32_e32 v147, 1.0, v147
	v_add_f32_e32 v148, 1.0, v148
	v_add_f32_e32 v149, 1.0, v149
	v_add_f32_e32 v150, 1.0, v150
	v_add_f32_e32 v151, 1.0, v151
	v_add_f32_e32 v152, 1.0, v152
	v_add_f32_e32 v153, 1.0, v153
	v_rcp_f32_e32 v146, v146
	v_rcp_f32_e32 v147, v147
	v_rcp_f32_e32 v148, v148
	v_rcp_f32_e32 v149, v149
	v_rcp_f32_e32 v150, v150
	v_rcp_f32_e32 v151, v151
	v_rcp_f32_e32 v152, v152
	v_rcp_f32_e32 v153, v153
	v_mul_f32_e32 v146, v78, v146
	v_mul_f32_e32 v147, v79, v147
	v_mul_f32_e32 v148, v80, v148
	v_mul_f32_e32 v149, v81, v149
	v_mul_f32_e32 v150, v70, v150
	v_mul_f32_e32 v151, v71, v151
	v_mul_f32_e32 v152, v72, v152
	v_mul_f32_e32 v153, v73, v153
	v_mul_f32_e32 v74, v74, v146
	v_mul_f32_e32 v75, v75, v147
	v_mul_f32_e32 v76, v76, v148
	v_mul_f32_e32 v77, v77, v149
	v_mul_f32_e32 v70, v66, v150
	v_mul_f32_e32 v71, v67, v151
	v_mul_f32_e32 v72, v68, v152
	v_mul_f32_e32 v69, v69, v153
	v_cvt_pk_bf16_f32 v66, v74, v75
	v_cvt_pk_bf16_f32 v67, v76, v77
	v_cvt_pk_bf16_f32 v68, v70, v71
	v_or_b32_e32 v70, 48, v142
	v_mad_i64_i32 v[70:71], s[30:31], v70, s19, v[114:115]
	v_lshl_add_u64 v[70:71], v[70:71], 0, v[116:117]
	v_cvt_pk_bf16_f32 v69, v72, v69
	global_store_dwordx4 v[70:71], v[66:69], off
	s_nop 1
	v_add_u32_e32 v66, 0x80, v142
	v_mul_f32_e32 v146, 0xbfb8aa3b, v62
	v_mul_f32_e32 v147, 0xbfb8aa3b, v63
	v_mul_f32_e32 v148, 0xbfb8aa3b, v64
	v_mul_f32_e32 v149, 0xbfb8aa3b, v65
	v_mul_f32_e32 v150, 0xbfb8aa3b, v54
	v_mul_f32_e32 v151, 0xbfb8aa3b, v55
	v_mul_f32_e32 v152, 0xbfb8aa3b, v56
	v_mul_f32_e32 v153, 0xbfb8aa3b, v57
	v_exp_f32_e32 v146, v146
	v_exp_f32_e32 v147, v147
	v_exp_f32_e32 v148, v148
	v_exp_f32_e32 v149, v149
	v_exp_f32_e32 v150, v150
	v_exp_f32_e32 v151, v151
	v_exp_f32_e32 v152, v152
	v_exp_f32_e32 v153, v153
	v_add_f32_e32 v146, 1.0, v146
	v_add_f32_e32 v147, 1.0, v147
	v_add_f32_e32 v148, 1.0, v148
	v_add_f32_e32 v149, 1.0, v149
	v_add_f32_e32 v150, 1.0, v150
	v_add_f32_e32 v151, 1.0, v151
	v_add_f32_e32 v152, 1.0, v152
	v_add_f32_e32 v153, 1.0, v153
	v_rcp_f32_e32 v146, v146
	v_rcp_f32_e32 v147, v147
	v_rcp_f32_e32 v148, v148
	v_rcp_f32_e32 v149, v149
	v_rcp_f32_e32 v150, v150
	v_rcp_f32_e32 v151, v151
	v_rcp_f32_e32 v152, v152
	v_rcp_f32_e32 v153, v153
	v_mul_f32_e32 v146, v62, v146
	v_mul_f32_e32 v147, v63, v147
	v_mul_f32_e32 v148, v64, v148
	v_mul_f32_e32 v149, v65, v149
	v_mul_f32_e32 v150, v54, v150
	v_mul_f32_e32 v151, v55, v151
	v_mul_f32_e32 v152, v56, v152
	v_mul_f32_e32 v153, v57, v153
	v_mul_f32_e32 v58, v58, v146
	v_mul_f32_e32 v59, v59, v147
	v_mul_f32_e32 v60, v60, v148
	v_mul_f32_e32 v61, v61, v149
	v_mul_f32_e32 v54, v50, v150
	v_mul_f32_e32 v55, v51, v151
	v_mul_f32_e32 v56, v52, v152
	v_mul_f32_e32 v53, v53, v153
	v_cvt_pk_bf16_f32 v50, v58, v59
	v_cvt_pk_bf16_f32 v51, v60, v61
	v_cvt_pk_bf16_f32 v52, v54, v55
	v_mad_i64_i32 v[54:55], s[30:31], v66, s19, v[114:115]
	v_lshl_add_u64 v[54:55], v[54:55], 0, v[116:117]
	v_cvt_pk_bf16_f32 v53, v56, v53
	global_store_dwordx4 v[54:55], v[50:53], off
	s_nop 1
	v_mul_f32_e32 v146, 0xbfb8aa3b, v46
	v_mul_f32_e32 v147, 0xbfb8aa3b, v47
	v_mul_f32_e32 v148, 0xbfb8aa3b, v48
	v_mul_f32_e32 v149, 0xbfb8aa3b, v49
	v_mul_f32_e32 v150, 0xbfb8aa3b, v38
	v_mul_f32_e32 v151, 0xbfb8aa3b, v39
	v_mul_f32_e32 v152, 0xbfb8aa3b, v40
	v_mul_f32_e32 v153, 0xbfb8aa3b, v41
	v_exp_f32_e32 v146, v146
	v_exp_f32_e32 v147, v147
	v_exp_f32_e32 v148, v148
	v_exp_f32_e32 v149, v149
	v_exp_f32_e32 v150, v150
	v_exp_f32_e32 v151, v151
	v_exp_f32_e32 v152, v152
	v_exp_f32_e32 v153, v153
	v_add_f32_e32 v146, 1.0, v146
	v_add_f32_e32 v147, 1.0, v147
	v_add_f32_e32 v148, 1.0, v148
	v_add_f32_e32 v149, 1.0, v149
	v_add_f32_e32 v150, 1.0, v150
	v_add_f32_e32 v151, 1.0, v151
	v_add_f32_e32 v152, 1.0, v152
	v_add_f32_e32 v153, 1.0, v153
	v_rcp_f32_e32 v146, v146
	v_rcp_f32_e32 v147, v147
; #define PG8_WAIT_V(n) asm volatile("s_waitcnt vmcnt(" #n ")" ::: "memory")
; template <class Epi, class Sched>
; __device__ __forceinline__ void gemm_phase(LAS unsigned char* lds, const int lda, const int ldb, const Sched& S, const Epi& E) {
;     ...
;     for (;;) {
;         const bool has_next = S.next(ui + 1, nxt);
;         const char* nA = has_next ? nxt.A : cA; const char* nB = has_next ? nxt.B : cB;
;         const int nt = cur.nt;
; #pragma unroll 1
;         for (int t = 0; t < nt; t += 2) {
;             const bool last = (t == nt - 2);
;             const char* a1 = cA + (size_t)(t + 1) * kstep;
;             const char* a2 = last ? nA : cA + (size_t)(t + 2) * kstep; const char* b2 = last ? nB : cB + (size_t)(t + 2) * kstep;
;             const char* a3 = a2 + kstep; const char* b3 = b2 + kstep;
;             PG8_LDB(B0, 0, 0); PG8_LDB(B1, 0, 1); PG8_SCHED; PG8_LDA(At, 0, 0); PG8_STAGE(PG8_SA(1, 1), a1 + hstepA, voffA);
;             PG8_WAIT_V(8); PG8_WAIT_L(0); PG8_BAR; PG8_MMA(0, 0, At, B0); PG8_MMA(0, 1, At, B1); PG8_BAR; PG8_SCHED;
;             PG8_LDA(At, 0, 1); PG8_STAGE(PG8_SB(0, 0), b2, voffB); PG8_STAGE(PG8_SB(0, 1), b2 + hstepB, voffB); PG8_STAGE(PG8_SA(0, 0), a2, voffA);
;             PG8_WAIT_V(8); PG8_WAIT_L(0); PG8_BAR; PG8_MMA(1, 0, At, B0); PG8_MMA(1, 1, At, B1); PG8_BAR; PG8_SCHED;
;             PG8_LDB(B0, 1, 0); PG8_LDB(B1, 1, 1); PG8_SCHED; PG8_LDA(At, 1, 0); PG8_STAGE(PG8_SA(0, 1), a2 + hstepA, voffA);
;             PG8_WAIT_V(8); PG8_WAIT_L(0); PG8_BAR; PG8_MMA(0, 0, At, B0); PG8_MMA(0, 1, At, B1); PG8_BAR; PG8_SCHED;
;     __device__ __forceinline__ void operator()(const Acc& acc, const Unit& u, int wr, int wc, int fr, int fq) const {
;         const int row0 = u.pm * 256 + wr * 64 + fr; const int col = u.pn * 128 + wc * 32 + 8 * fq;
; #pragma unroll
;         for (int ai = 0; ai < 2; ++ai)
; #pragma unroll
;             for (int m = 0; m < 4; ++m) {
;                 float o[8];
; #pragma unroll
;                 for (int j = 0; j < 8; ++j) { const float g = acc[ai][0][m][j >> 2][j & 3], up = acc[ai][1][m][j >> 2][j & 3]; o[j] = g * sigmoidf_(g) * up; }
;                 u32x4 w; w.x = cvt_pk_bf16(o[0], o[1]); w.y = cvt_pk_bf16(o[2], o[3]); w.z = cvt_pk_bf16(o[4], o[5]); w.w = cvt_pk_bf16(o[6], o[7]);
;                 *(u32x4*)(hid + (size_t)(row0 + ai * 128 + m * 16) * DFF + col) = w;
;             }
	v_rcp_f32_e32 v148, v148
	v_rcp_f32_e32 v149, v149
	v_rcp_f32_e32 v150, v150
	v_rcp_f32_e32 v151, v151
	v_rcp_f32_e32 v152, v152
	v_rcp_f32_e32 v153, v153
	v_mul_f32_e32 v146, v46, v146
	v_mul_f32_e32 v147, v47, v147
	v_mul_f32_e32 v148, v48, v148
	v_mul_f32_e32 v149, v49, v149
	v_mul_f32_e32 v150, v38, v150
	v_mul_f32_e32 v151, v39, v151
	v_mul_f32_e32 v152, v40, v152
	v_mul_f32_e32 v153, v41, v153
	v_mul_f32_e32 v42, v42, v146
	v_mul_f32_e32 v43, v43, v147
	v_mul_f32_e32 v44, v44, v148
	v_mul_f32_e32 v45, v45, v149
	v_mul_f32_e32 v38, v34, v150
	v_mul_f32_e32 v39, v35, v151
	v_mul_f32_e32 v40, v36, v152
	v_mul_f32_e32 v37, v37, v153
	v_cvt_pk_bf16_f32 v34, v42, v43
	v_cvt_pk_bf16_f32 v35, v44, v45
	v_cvt_pk_bf16_f32 v36, v38, v39
	v_add_u32_e32 v38, 0x90, v142
	v_mad_i64_i32 v[38:39], s[30:31], v38, s19, v[114:115]
	v_lshl_add_u64 v[38:39], v[38:39], 0, v[116:117]
	v_cvt_pk_bf16_f32 v37, v40, v37
	global_store_dwordx4 v[38:39], v[34:37], off
	s_nop 1
	v_mul_f32_e32 v146, 0xbfb8aa3b, v30
	v_mul_f32_e32 v147, 0xbfb8aa3b, v31
	v_mul_f32_e32 v148, 0xbfb8aa3b, v32
	v_mul_f32_e32 v149, 0xbfb8aa3b, v33
	v_mul_f32_e32 v150, 0xbfb8aa3b, v22
	v_mul_f32_e32 v151, 0xbfb8aa3b, v23
	v_mul_f32_e32 v152, 0xbfb8aa3b, v24
	v_mul_f32_e32 v153, 0xbfb8aa3b, v25
	v_exp_f32_e32 v146, v146
	v_exp_f32_e32 v147, v147
	v_exp_f32_e32 v148, v148
	v_exp_f32_e32 v149, v149
	v_exp_f32_e32 v150, v150
	v_exp_f32_e32 v151, v151
	v_exp_f32_e32 v152, v152
	v_exp_f32_e32 v153, v153
	v_add_f32_e32 v146, 1.0, v146
	v_add_f32_e32 v147, 1.0, v147
	v_add_f32_e32 v148, 1.0, v148
	v_add_f32_e32 v149, 1.0, v149
	v_add_f32_e32 v150, 1.0, v150
	v_add_f32_e32 v151, 1.0, v151
	v_add_f32_e32 v152, 1.0, v152
	v_add_f32_e32 v153, 1.0, v153
	v_rcp_f32_e32 v146, v146
	v_rcp_f32_e32 v147, v147
	v_rcp_f32_e32 v148, v148
	v_rcp_f32_e32 v149, v149
	v_rcp_f32_e32 v150, v150
	v_rcp_f32_e32 v151, v151
	v_rcp_f32_e32 v152, v152
	v_rcp_f32_e32 v153, v153
	v_mul_f32_e32 v146, v30, v146
	v_mul_f32_e32 v147, v31, v147
	v_mul_f32_e32 v148, v32, v148
	v_mul_f32_e32 v149, v33, v149
	v_mul_f32_e32 v150, v22, v150
	v_mul_f32_e32 v151, v23, v151
	v_mul_f32_e32 v152, v24, v152
	v_mul_f32_e32 v153, v25, v153
	v_mul_f32_e32 v26, v26, v146
	v_mul_f32_e32 v27, v27, v147
	v_mul_f32_e32 v28, v28, v148
	v_mul_f32_e32 v29, v29, v149
	v_mul_f32_e32 v22, v18, v150
	v_mul_f32_e32 v23, v19, v151
	v_mul_f32_e32 v24, v20, v152
	v_mul_f32_e32 v21, v21, v153
	v_cvt_pk_bf16_f32 v18, v26, v27
	v_cvt_pk_bf16_f32 v19, v28, v29
	v_cvt_pk_bf16_f32 v20, v22, v23
	v_add_u32_e32 v22, 0xa0, v142
	v_mad_i64_i32 v[22:23], s[30:31], v22, s19, v[114:115]
	v_lshl_add_u64 v[22:23], v[22:23], 0, v[116:117]
	v_cvt_pk_bf16_f32 v21, v24, v21
	global_store_dwordx4 v[22:23], v[18:21], off
	s_nop 1
	v_mul_f32_e32 v146, 0xbfb8aa3b, v14
	v_mul_f32_e32 v147, 0xbfb8aa3b, v15
	v_mul_f32_e32 v148, 0xbfb8aa3b, v16
	v_mul_f32_e32 v149, 0xbfb8aa3b, v17
	v_mul_f32_e32 v150, 0xbfb8aa3b, v6
	v_mul_f32_e32 v151, 0xbfb8aa3b, v7
	v_mul_f32_e32 v152, 0xbfb8aa3b, v8
	v_mul_f32_e32 v153, 0xbfb8aa3b, v9
	v_exp_f32_e32 v146, v146
	v_exp_f32_e32 v147, v147
	v_exp_f32_e32 v148, v148
	v_exp_f32_e32 v149, v149
	v_exp_f32_e32 v150, v150
	v_exp_f32_e32 v151, v151
	v_exp_f32_e32 v152, v152
	v_exp_f32_e32 v153, v153
	v_add_f32_e32 v146, 1.0, v146
	v_add_f32_e32 v147, 1.0, v147
	v_add_f32_e32 v148, 1.0, v148
	v_add_f32_e32 v149, 1.0, v149
	v_add_f32_e32 v150, 1.0, v150
	v_add_f32_e32 v151, 1.0, v151
	v_add_f32_e32 v152, 1.0, v152
	v_add_f32_e32 v153, 1.0, v153
	v_rcp_f32_e32 v146, v146
	v_rcp_f32_e32 v147, v147
	v_rcp_f32_e32 v148, v148
	v_rcp_f32_e32 v149, v149
	v_rcp_f32_e32 v150, v150
	v_rcp_f32_e32 v151, v151
	v_rcp_f32_e32 v152, v152
	v_rcp_f32_e32 v153, v153
	v_mul_f32_e32 v146, v14, v146
	v_mul_f32_e32 v147, v15, v147
	v_mul_f32_e32 v148, v16, v148
	v_mul_f32_e32 v149, v17, v149
	v_mul_f32_e32 v150, v6, v150
	v_mul_f32_e32 v151, v7, v151
	v_mul_f32_e32 v152, v8, v152
	v_mul_f32_e32 v153, v9, v153
	v_mul_f32_e32 v10, v10, v146
	v_mul_f32_e32 v11, v11, v147
	v_mul_f32_e32 v12, v12, v148
	v_mul_f32_e32 v13, v13, v149
	v_mul_f32_e32 v6, v2, v150
	v_mul_f32_e32 v7, v3, v151
	v_mul_f32_e32 v8, v4, v152
	v_mul_f32_e32 v5, v5, v153
	v_cvt_pk_bf16_f32 v2, v10, v11
	v_cvt_pk_bf16_f32 v3, v12, v13
	v_cvt_pk_bf16_f32 v4, v6, v7
	v_add_u32_e32 v6, 0xb0, v142
	v_mad_i64_i32 v[6:7], s[30:31], v6, s19, v[114:115]
	v_lshl_add_u64 v[6:7], v[6:7], 0, v[116:117]
	s_mov_b64 s[30:31], -1
	v_cvt_pk_bf16_f32 v5, v8, v5
	global_store_dwordx4 v[6:7], v[2:5], off
	s_cbranch_vccnz .LBB0_1641
	s_andn2_b64 vcc, exec, s[0:1]
	s_cbranch_vccnz .LBB0_1640
	s_barrier
	s_branch .LBB0_1640
